# phase8 (final LayerNorm) row loop software-pipelined: next trip's 16 x/sub loads issued into a second register set before the current rows' math, copied at the loop top
# baseline (speedup 1.0000x reference)
.LBB0_1317:
	s_or_b64 exec, exec, s[0:1]
	s_waitcnt lgkmcnt(0)
	v_mov_b32_e32 v0, v174
	s_barrier
	v_readlane_b32 s0, v240, 17
	v_ashrrev_i32_e32 v1, 5, v174
	v_and_b32_e32 v1, -2, v1
	v_add_u32_e32 v8, s0, v1
	s_mov_b32 s0, 0x8000
	v_cmp_gt_i32_e32 vcc, s0, v8
	s_and_saveexec_b64 s[0:1], vcc
	s_cbranch_execz .LBB0_1320
	v_and_b32_e32 v1, 64, v175
	v_add_u32_e32 v1, 64, v1
	v_xor_b32_e32 v3, 32, v175
	v_cmp_lt_i32_e32 vcc, v3, v1
	v_and_b32_e32 v0, 63, v0
	v_mov_b32_e32 v11, 0
	v_cndmask_b32_e32 v3, v175, v3, vcc
	v_lshlrev_b32_e32 v29, 2, v3
	v_xor_b32_e32 v3, 16, v175
	v_cmp_lt_i32_e32 vcc, v3, v1
	v_readlane_b32 s36, v241, 17
	v_or_b32_e32 v2, 64, v0
	v_cndmask_b32_e32 v3, v175, v3, vcc
	v_lshlrev_b32_e32 v34, 2, v3
	v_xor_b32_e32 v3, 8, v175
	v_cmp_lt_i32_e32 vcc, v3, v1
	v_or_b32_e32 v4, 0x80, v0
	v_or_b32_e32 v6, 0xc0, v0
	v_cndmask_b32_e32 v3, v175, v3, vcc
	v_lshlrev_b32_e32 v35, 2, v3
	v_xor_b32_e32 v3, 4, v175
	v_cmp_lt_i32_e32 vcc, v3, v1
	v_lshlrev_b32_e32 v10, 4, v0
	v_readlane_b32 s37, v241, 18
	v_cndmask_b32_e32 v3, v175, v3, vcc
	v_lshlrev_b32_e32 v36, 2, v3
	v_xor_b32_e32 v3, 2, v175
	v_cmp_lt_i32_e32 vcc, v3, v1
	v_lshlrev_b32_e32 v18, 3, v0
	v_mov_b32_e32 v19, v11
	v_cndmask_b32_e32 v3, v175, v3, vcc
	v_lshlrev_b32_e32 v37, 2, v3
	v_xor_b32_e32 v3, 1, v175
	v_cmp_lt_i32_e32 vcc, v3, v1
	s_lshl_b32 s5, s88, 4
	v_lshl_add_u64 v[12:13], s[30:31], 0, v[10:11]
	v_cndmask_b32_e32 v1, v175, v3, vcc
	v_lshlrev_b32_e32 v38, 2, v1
	v_lshl_add_u64 v[14:15], s[16:17], 0, v[10:11]
	v_lshl_add_u64 v[16:17], s[36:37], 0, v[10:11]
	v_lshl_add_u64 v[18:19], s[66:67], 0, v[18:19]
	v_lshl_add_u64 v[20:21], s[18:19], 0, v[10:11]
	s_mov_b64 s[0:1], 0
	s_mov_b64 s[2:3], 0x2000
	v_lshlrev_b32_e32 v10, 4, v0
	v_lshlrev_b32_e32 v22, 4, v2
	v_mov_b32_e32 v23, v11
	v_lshlrev_b32_e32 v24, 4, v4
	v_mov_b32_e32 v25, v11
	v_lshlrev_b32_e32 v26, 4, v6
	v_mov_b32_e32 v27, v11
	s_mov_b32 s4, 0x3f9837f0
	s_mov_b32 s6, 0x3a800000
	v_mov_b32_e32 v28, 0x3727c5ac
	s_mov_b32 s7, 0x800000
	s_movk_i32 s8, 0x7fff
	v_readlane_b32 s38, v241, 19
	v_readlane_b32 s39, v241, 20
	v_readlane_b32 s40, v241, 21
	v_readlane_b32 s41, v241, 22
	v_readlane_b32 s42, v241, 23
	v_readlane_b32 s43, v241, 24
	v_readlane_b32 s44, v241, 25
	v_readlane_b32 s45, v241, 26
	v_readlane_b32 s46, v241, 27
	v_readlane_b32 s47, v241, 28
	v_readlane_b32 s48, v241, 29
	v_readlane_b32 s49, v241, 30
	v_readlane_b32 s50, v241, 31
	v_readlane_b32 s51, v241, 32
	global_load_dwordx4 v[176:179], v[12:13], off
	global_load_dwordx4 v[180:183], v[12:13], off offset:1024
	global_load_dwordx4 v[184:187], v[12:13], off offset:2048
	global_load_dwordx4 v[188:191], v[12:13], off offset:3072
	global_load_dwordx4 v[192:195], v[14:15], off
	global_load_dwordx4 v[196:199], v[14:15], off offset:1024
	global_load_dwordx4 v[200:203], v[14:15], off offset:2048
	global_load_dwordx4 v[204:207], v[14:15], off offset:3072
	v_ashrrev_i32_e32 v9, 31, v8
	v_add_u32_e32 v212, 1, v8
	v_ashrrev_i32_e32 v213, 31, v212
	v_lshlrev_b64 v[216:217], 11, v[8:9]
	v_lshlrev_b64 v[218:219], 12, v[8:9]
	v_lshlrev_b64 v[222:223], 11, v[212:213]
	v_lshlrev_b64 v[224:225], 12, v[212:213]
	v_lshl_add_u64 v[216:217], v[18:19], 0, v[216:217]
	v_lshl_add_u64 v[218:219], v[16:17], 0, v[218:219]
	v_lshl_add_u64 v[222:223], v[18:19], 0, v[222:223]
	v_lshl_add_u64 v[224:225], v[16:17], 0, v[224:225]
	global_load_dwordx2 v[152:153], v[216:217], off
	global_load_dwordx2 v[154:155], v[216:217], off offset:512
	global_load_dwordx2 v[156:157], v[216:217], off offset:1024
	global_load_dwordx2 v[158:159], v[216:217], off offset:1536
	global_load_dwordx4 v[120:123], v[218:219], off
	global_load_dwordx4 v[124:127], v[218:219], off offset:1024
	global_load_dwordx4 v[128:131], v[218:219], off offset:2048
	global_load_dwordx4 v[132:135], v[218:219], off offset:3072
	global_load_dwordx2 v[160:161], v[222:223], off
	global_load_dwordx2 v[162:163], v[222:223], off offset:512
	global_load_dwordx2 v[164:165], v[222:223], off offset:1024
	global_load_dwordx2 v[166:167], v[222:223], off offset:1536
	global_load_dwordx4 v[136:139], v[224:225], off
	global_load_dwordx4 v[140:143], v[224:225], off offset:1024
	global_load_dwordx4 v[144:147], v[224:225], off offset:2048
	global_load_dwordx4 v[148:151], v[224:225], off offset:3072
	s_waitcnt vmcnt(0)
.LBB0_1319:
	s_waitcnt vmcnt(8)
	v_ashrrev_i32_e32 v208, 12, v8
	v_mul_i32_i24_e32 v210, 0xc00, v208
	v_ashrrev_i32_e32 v9, 31, v8
	v_add_u32_e32 v212, 1, v8
	v_ashrrev_i32_e32 v211, 31, v210
	v_ashrrev_i32_e32 v213, 31, v212
	v_lshl_add_u64 v[214:215], v[210:211], 2, s[20:21]
	v_lshlrev_b64 v[216:217], 12, v[8:9]
	v_lshlrev_b64 v[218:219], 12, v[212:213]
	v_lshl_add_u64 v[220:221], v[214:215], 0, s[2:3]
	v_lshl_add_u64 v[104:105], v[220:221], 0, v[10:11]
	v_lshl_add_u64 v[106:107], v[220:221], 0, v[22:23]
	v_lshl_add_u64 v[108:109], v[220:221], 0, v[24:25]
	v_lshl_add_u64 v[110:111], v[220:221], 0, v[26:27]
	v_lshl_add_u64 v[32:33], v[20:21], 0, v[216:217]
	v_lshl_add_u64 v[30:31], v[20:21], 0, v[218:219]
	global_load_dwordx4 v[72:75], v[104:105], off
	global_load_dwordx4 v[76:79], v[106:107], off
	global_load_dwordx4 v[80:83], v[108:109], off
	global_load_dwordx4 v[84:87], v[110:111], off
	v_mov_b32_e32 v0, v176
	v_mov_b32_e32 v1, v177
	v_mov_b32_e32 v2, v178
	v_mov_b32_e32 v3, v179
	v_mov_b32_e32 v4, v192
	v_mov_b32_e32 v5, v193
	v_mov_b32_e32 v6, v194
	v_mov_b32_e32 v7, v195
	v_mov_b64_e32 v[88:89], v[152:153]
	v_mov_b64_e32 v[90:91], v[154:155]
	v_mov_b64_e32 v[92:93], v[156:157]
	v_mov_b64_e32 v[94:95], v[158:159]
	v_mov_b64_e32 v[96:97], v[160:161]
	v_mov_b64_e32 v[98:99], v[162:163]
	v_mov_b64_e32 v[100:101], v[164:165]
	v_mov_b64_e32 v[102:103], v[166:167]
	v_mov_b64_e32 v[40:41], v[120:121]
	v_mov_b64_e32 v[42:43], v[122:123]
	v_mov_b64_e32 v[44:45], v[124:125]
	v_mov_b64_e32 v[46:47], v[126:127]
	v_mov_b64_e32 v[48:49], v[128:129]
	v_mov_b64_e32 v[50:51], v[130:131]
	v_mov_b64_e32 v[52:53], v[132:133]
	v_mov_b64_e32 v[54:55], v[134:135]
	v_mov_b64_e32 v[56:57], v[136:137]
	v_mov_b64_e32 v[58:59], v[138:139]
	v_mov_b64_e32 v[60:61], v[140:141]
	v_mov_b64_e32 v[62:63], v[142:143]
	v_mov_b64_e32 v[64:65], v[144:145]
	v_mov_b64_e32 v[66:67], v[146:147]
	v_mov_b64_e32 v[68:69], v[148:149]
	v_mov_b64_e32 v[70:71], v[150:151]
	v_add_u32_e32 v8, s5, v8
	v_cmp_lt_i32_e32 vcc, s8, v8
	s_cbranch_vccnz .Lp8_last_rows
	v_ashrrev_i32_e32 v9, 31, v8
	v_add_u32_e32 v212, 1, v8
	v_ashrrev_i32_e32 v213, 31, v212
	v_lshlrev_b64 v[216:217], 11, v[8:9]
	v_lshlrev_b64 v[218:219], 12, v[8:9]
	v_lshlrev_b64 v[222:223], 11, v[212:213]
	v_lshlrev_b64 v[224:225], 12, v[212:213]
	v_lshl_add_u64 v[216:217], v[18:19], 0, v[216:217]
	v_lshl_add_u64 v[218:219], v[16:17], 0, v[218:219]
	v_lshl_add_u64 v[222:223], v[18:19], 0, v[222:223]
	v_lshl_add_u64 v[224:225], v[16:17], 0, v[224:225]
	global_load_dwordx2 v[152:153], v[216:217], off
	global_load_dwordx2 v[154:155], v[216:217], off offset:512
	global_load_dwordx2 v[156:157], v[216:217], off offset:1024
	global_load_dwordx2 v[158:159], v[216:217], off offset:1536
	global_load_dwordx4 v[120:123], v[218:219], off
	global_load_dwordx4 v[124:127], v[218:219], off offset:1024
	global_load_dwordx4 v[128:131], v[218:219], off offset:2048
	global_load_dwordx4 v[132:135], v[218:219], off offset:3072
	global_load_dwordx2 v[160:161], v[222:223], off
	global_load_dwordx2 v[162:163], v[222:223], off offset:512
	global_load_dwordx2 v[164:165], v[222:223], off offset:1024
	global_load_dwordx2 v[166:167], v[222:223], off offset:1536
	global_load_dwordx4 v[136:139], v[224:225], off
	global_load_dwordx4 v[140:143], v[224:225], off offset:1024
	global_load_dwordx4 v[144:147], v[224:225], off offset:2048
	global_load_dwordx4 v[148:151], v[224:225], off offset:3072
	s_branch .Lp8_math

.Lp8_math:
	s_nop 0
	v_lshlrev_b32_e32 v116, 16, v100
	v_lshlrev_b32_e32 v104, 16, v88
	v_and_b32_e32 v105, 0xffff0000, v88
	v_lshlrev_b32_e32 v106, 16, v90
	v_and_b32_e32 v107, 0xffff0000, v90
	v_lshlrev_b32_e32 v112, 16, v96
	v_and_b32_e32 v113, 0xffff0000, v96
	v_lshlrev_b32_e32 v114, 16, v98
	v_and_b32_e32 v115, 0xffff0000, v98
	v_and_b32_e32 v117, 0xffff0000, v100
	s_nop 0
	v_lshlrev_b32_e32 v118, 16, v102
	v_and_b32_e32 v119, 0xffff0000, v102
	s_waitcnt vmcnt(19)
	v_pk_add_f32 v[72:73], v[72:73], 1.0 op_sel_hi:[1,0]
	s_waitcnt vmcnt(18)
	v_pk_add_f32 v[76:77], v[76:77], 1.0 op_sel_hi:[1,0]
	s_waitcnt vmcnt(17)
	v_pk_add_f32 v[80:81], v[80:81], 1.0 op_sel_hi:[1,0]
	s_waitcnt vmcnt(16)
	v_pk_add_f32 v[84:85], v[84:85], 1.0 op_sel_hi:[1,0]
	v_lshlrev_b32_e32 v88, 16, v89
	v_and_b32_e32 v89, 0xffff0000, v89
	v_lshlrev_b32_e32 v90, 16, v91
	v_and_b32_e32 v91, 0xffff0000, v91
	v_lshlrev_b32_e32 v108, 16, v92
	v_and_b32_e32 v109, 0xffff0000, v92
	v_lshlrev_b32_e32 v92, 16, v93
	v_and_b32_e32 v93, 0xffff0000, v93
	v_lshlrev_b32_e32 v96, 16, v97
	v_and_b32_e32 v97, 0xffff0000, v97
	v_lshlrev_b32_e32 v98, 16, v99
	v_and_b32_e32 v99, 0xffff0000, v99
	v_lshlrev_b32_e32 v100, 16, v101
	v_and_b32_e32 v101, 0xffff0000, v101
	v_pk_add_f32 v[74:75], v[74:75], 1.0 op_sel_hi:[1,0]
	v_pk_add_f32 v[78:79], v[78:79], 1.0 op_sel_hi:[1,0]
	v_pk_add_f32 v[82:83], v[82:83], 1.0 op_sel_hi:[1,0]
	v_pk_mul_f32 v[112:113], v[72:73], v[112:113]
	v_pk_mul_f32 v[114:115], v[76:77], v[114:115]
	v_pk_mul_f32 v[116:117], v[80:81], v[116:117]
	v_pk_mul_f32 v[118:119], v[84:85], v[118:119]
	v_pk_mul_f32 v[72:73], v[72:73], v[104:105]
	v_pk_mul_f32 v[76:77], v[76:77], v[106:107]
	v_lshlrev_b32_e32 v110, 16, v94
	v_and_b32_e32 v111, 0xffff0000, v94
	v_pk_mul_f32 v[96:97], v[74:75], v[96:97]
	v_pk_mul_f32 v[98:99], v[78:79], v[98:99]
	v_pk_mul_f32 v[100:101], v[82:83], v[100:101]
	v_pk_mul_f32 v[74:75], v[74:75], v[88:89]
	v_pk_mul_f32 v[78:79], v[78:79], v[90:91]
	v_pk_mul_f32 v[80:81], v[80:81], v[108:109]
	v_pk_mul_f32 v[82:83], v[82:83], v[92:93]
	v_pk_fma_f32 v[56:57], v[56:57], s[4:5], v[112:113] op_sel_hi:[1,0,1]
	v_pk_fma_f32 v[60:61], v[60:61], s[4:5], v[114:115] op_sel_hi:[1,0,1]
	v_pk_fma_f32 v[64:65], v[64:65], s[4:5], v[116:117] op_sel_hi:[1,0,1]
	v_pk_fma_f32 v[68:69], v[68:69], s[4:5], v[118:119] op_sel_hi:[1,0,1]
	v_pk_fma_f32 v[40:41], v[40:41], s[4:5], v[72:73] op_sel_hi:[1,0,1]
	v_pk_fma_f32 v[44:45], v[44:45], s[4:5], v[76:77] op_sel_hi:[1,0,1]
	v_lshlrev_b32_e32 v94, 16, v95
	v_and_b32_e32 v95, 0xffff0000, v95
	v_lshlrev_b32_e32 v102, 16, v103
	v_and_b32_e32 v103, 0xffff0000, v103
	v_pk_add_f32 v[86:87], v[86:87], 1.0 op_sel_hi:[1,0]
	v_pk_mul_f32 v[84:85], v[84:85], v[110:111]
	v_pk_fma_f32 v[58:59], v[58:59], s[4:5], v[96:97] op_sel_hi:[1,0,1]
	v_pk_fma_f32 v[62:63], v[62:63], s[4:5], v[98:99] op_sel_hi:[1,0,1]
	v_pk_fma_f32 v[42:43], v[42:43], s[4:5], v[74:75] op_sel_hi:[1,0,1]
	v_pk_fma_f32 v[46:47], v[46:47], s[4:5], v[78:79] op_sel_hi:[1,0,1]
	v_pk_fma_f32 v[48:49], v[48:49], s[4:5], v[80:81] op_sel_hi:[1,0,1]
	v_pk_fma_f32 v[50:51], v[50:51], s[4:5], v[82:83] op_sel_hi:[1,0,1]
	v_mov_b32_e32 v72, v56
	v_mov_b32_e32 v73, v60
	v_mov_b32_e32 v74, v57
	v_mov_b32_e32 v75, v61
	v_mov_b32_e32 v80, v64
	v_mov_b32_e32 v81, v68
	v_mov_b32_e32 v82, v65
	v_mov_b32_e32 v83, v69
	v_mov_b32_e32 v88, v40
	v_mov_b32_e32 v89, v44
	v_mov_b32_e32 v90, v41
	v_mov_b32_e32 v91, v45
	v_pk_mul_f32 v[102:103], v[86:87], v[102:103]
	v_pk_mul_f32 v[86:87], v[86:87], v[94:95]
	v_pk_fma_f32 v[52:53], v[52:53], s[4:5], v[84:85] op_sel_hi:[1,0,1]
	v_mov_b32_e32 v76, v58
	v_mov_b32_e32 v77, v62
	v_mov_b32_e32 v92, v42
	v_mov_b32_e32 v93, v46
	v_pk_add_f32 v[72:73], v[72:73], v[74:75]
	v_pk_add_f32 v[74:75], v[80:81], v[82:83]
	v_pk_add_f32 v[80:81], v[88:89], v[90:91]
	v_pk_fma_f32 v[66:67], v[66:67], s[4:5], v[100:101] op_sel_hi:[1,0,1]
	v_pk_fma_f32 v[70:71], v[70:71], s[4:5], v[102:103] op_sel_hi:[1,0,1]
	v_pk_fma_f32 v[54:55], v[54:55], s[4:5], v[86:87] op_sel_hi:[1,0,1]
	v_mov_b32_e32 v78, v59
	v_mov_b32_e32 v79, v63
	v_mov_b32_e32 v94, v43
	v_mov_b32_e32 v95, v47
	v_mov_b32_e32 v96, v48
	v_mov_b32_e32 v97, v52
	v_mov_b32_e32 v98, v49
	v_mov_b32_e32 v99, v53
	v_pk_add_f32 v[72:73], v[72:73], v[76:77]
	v_pk_add_f32 v[76:77], v[80:81], v[92:93]
	v_mov_b32_e32 v84, v66
	v_mov_b32_e32 v85, v70
	v_mov_b32_e32 v100, v50
	v_mov_b32_e32 v101, v54
	v_pk_add_f32 v[82:83], v[96:97], v[98:99]
	v_pk_add_f32 v[72:73], v[78:79], v[72:73]
	v_pk_add_f32 v[76:77], v[76:77], v[94:95]
	v_mov_b32_e32 v86, v67
	v_mov_b32_e32 v87, v71
	v_mov_b32_e32 v102, v51
	v_mov_b32_e32 v103, v55
	v_pk_add_f32 v[74:75], v[74:75], v[84:85]
	v_pk_add_f32 v[80:81], v[82:83], v[100:101]
	v_add_f32_e32 v9, 0, v72
	v_add_f32_e32 v39, 0, v76
	v_pk_add_f32 v[74:75], v[86:87], v[74:75]
	v_pk_add_f32 v[78:79], v[80:81], v[102:103]
	v_add_f32_e32 v9, v9, v73
	v_add_f32_e32 v39, v39, v77
	v_add_f32_e32 v9, v9, v74
	v_add_f32_e32 v39, v39, v78
	v_add_f32_e32 v39, v39, v79
	v_add_f32_e32 v9, v9, v75
	ds_bpermute_b32 v72, v29, v39
	ds_bpermute_b32 v73, v29, v9
	s_waitcnt lgkmcnt(1)
	v_add_f32_e32 v39, v39, v72
	s_waitcnt lgkmcnt(0)
	v_add_f32_e32 v9, v9, v73
	ds_bpermute_b32 v72, v34, v39
	ds_bpermute_b32 v73, v34, v9
	s_waitcnt lgkmcnt(1)
	v_add_f32_e32 v39, v39, v72
	s_waitcnt lgkmcnt(0)
	v_add_f32_e32 v9, v9, v73
	ds_bpermute_b32 v72, v35, v39
	ds_bpermute_b32 v73, v35, v9
	s_waitcnt lgkmcnt(1)
	v_add_f32_e32 v39, v39, v72
	s_waitcnt lgkmcnt(0)
	v_add_f32_e32 v9, v9, v73
	ds_bpermute_b32 v72, v36, v39
	ds_bpermute_b32 v73, v36, v9
	s_waitcnt lgkmcnt(1)
	v_add_f32_e32 v39, v39, v72
	s_waitcnt lgkmcnt(0)
	v_add_f32_e32 v9, v9, v73
	ds_bpermute_b32 v72, v37, v39
	ds_bpermute_b32 v73, v37, v9
	s_waitcnt lgkmcnt(1)
	v_add_f32_e32 v39, v39, v72
	s_waitcnt lgkmcnt(0)
	v_add_f32_e32 v9, v9, v73
	ds_bpermute_b32 v72, v38, v39
	ds_bpermute_b32 v73, v38, v9
	s_waitcnt lgkmcnt(1)
	v_add_f32_e32 v39, v39, v72
	s_waitcnt lgkmcnt(0)
	v_add_f32_e32 v9, v9, v73
	v_mul_f32_e32 v72, 0x3a800000, v39
	v_mul_f32_e32 v74, 0x3a800000, v9
	v_pk_add_f32 v[40:41], v[40:41], v[72:73] op_sel_hi:[1,0] neg_lo:[0,1] neg_hi:[0,1]
	v_pk_add_f32 v[44:45], v[44:45], v[72:73] op_sel_hi:[1,0] neg_lo:[0,1] neg_hi:[0,1]
	v_pk_add_f32 v[48:49], v[48:49], v[72:73] op_sel_hi:[1,0] neg_lo:[0,1] neg_hi:[0,1]
	v_pk_add_f32 v[52:53], v[52:53], v[72:73] op_sel_hi:[1,0] neg_lo:[0,1] neg_hi:[0,1]
	v_pk_add_f32 v[56:57], v[56:57], v[74:75] op_sel_hi:[1,0] neg_lo:[0,1] neg_hi:[0,1]
	v_pk_add_f32 v[60:61], v[60:61], v[74:75] op_sel_hi:[1,0] neg_lo:[0,1] neg_hi:[0,1]
	v_pk_add_f32 v[58:59], v[58:59], v[74:75] op_sel_hi:[1,0] neg_lo:[0,1] neg_hi:[0,1]
	v_pk_add_f32 v[62:63], v[62:63], v[74:75] op_sel_hi:[1,0] neg_lo:[0,1] neg_hi:[0,1]
	v_pk_add_f32 v[64:65], v[64:65], v[74:75] op_sel_hi:[1,0] neg_lo:[0,1] neg_hi:[0,1]
	v_pk_add_f32 v[66:67], v[66:67], v[74:75] op_sel_hi:[1,0] neg_lo:[0,1] neg_hi:[0,1]
	v_pk_add_f32 v[68:69], v[68:69], v[74:75] op_sel_hi:[1,0] neg_lo:[0,1] neg_hi:[0,1]
	v_pk_add_f32 v[70:71], v[70:71], v[74:75] op_sel_hi:[1,0] neg_lo:[0,1] neg_hi:[0,1]
	v_mov_b32_e32 v74, v41
	v_mov_b32_e32 v75, v45
	v_mov_b32_e32 v82, v53
	v_mov_b32_e32 v83, v49
	v_mov_b32_e32 v90, v57
	v_mov_b32_e32 v91, v61
	v_pk_add_f32 v[42:43], v[42:43], v[72:73] op_sel_hi:[1,0] neg_lo:[0,1] neg_hi:[0,1]
	v_pk_add_f32 v[46:47], v[46:47], v[72:73] op_sel_hi:[1,0] neg_lo:[0,1] neg_hi:[0,1]
	v_pk_add_f32 v[50:51], v[50:51], v[72:73] op_sel_hi:[1,0] neg_lo:[0,1] neg_hi:[0,1]
	v_pk_add_f32 v[54:55], v[54:55], v[72:73] op_sel_hi:[1,0] neg_lo:[0,1] neg_hi:[0,1]
	v_mov_b32_e32 v72, v40
	v_mov_b32_e32 v73, v44
	v_mov_b32_e32 v80, v52
	v_mov_b32_e32 v81, v48
	v_mov_b32_e32 v88, v56
	v_mov_b32_e32 v89, v60
	v_mov_b32_e32 v98, v69
	v_mov_b32_e32 v99, v65
	v_pk_mul_f32 v[74:75], v[74:75], v[74:75]
	v_pk_mul_f32 v[82:83], v[82:83], v[82:83]
	v_pk_mul_f32 v[90:91], v[90:91], v[90:91]
	v_mov_b32_e32 v76, v42
	v_mov_b32_e32 v77, v46
	v_mov_b32_e32 v92, v58
	v_mov_b32_e32 v93, v62
	v_mov_b32_e32 v96, v68
	v_mov_b32_e32 v97, v64
	v_pk_mul_f32 v[98:99], v[98:99], v[98:99]
	v_pk_fma_f32 v[72:73], v[72:73], v[72:73], v[74:75]
	v_pk_fma_f32 v[74:75], v[80:81], v[80:81], v[82:83]
	v_pk_fma_f32 v[80:81], v[88:89], v[88:89], v[90:91]
	v_mov_b32_e32 v78, v43
	v_mov_b32_e32 v79, v47
	v_mov_b32_e32 v84, v54
	v_mov_b32_e32 v85, v50
	v_mov_b32_e32 v94, v59
	v_mov_b32_e32 v95, v63
	v_mov_b32_e32 v100, v70
	v_mov_b32_e32 v101, v66
	v_pk_fma_f32 v[82:83], v[96:97], v[96:97], v[98:99]
	v_pk_fma_f32 v[72:73], v[76:77], v[76:77], v[72:73]
	v_pk_fma_f32 v[76:77], v[92:93], v[92:93], v[80:81]
	v_mov_b32_e32 v86, v55
	v_mov_b32_e32 v87, v51
	v_mov_b32_e32 v102, v71
	v_mov_b32_e32 v103, v67
	v_pk_fma_f32 v[74:75], v[84:85], v[84:85], v[74:75]
	v_pk_fma_f32 v[80:81], v[100:101], v[100:101], v[82:83]
	v_pk_fma_f32 v[72:73], v[78:79], v[78:79], v[72:73]
	v_pk_fma_f32 v[76:77], v[94:95], v[94:95], v[76:77]
	v_pk_fma_f32 v[74:75], v[86:87], v[86:87], v[74:75]
	v_pk_fma_f32 v[78:79], v[102:103], v[102:103], v[80:81]
	v_mov_b32_e32 v80, v76
	v_mov_b32_e32 v81, v72
	v_mov_b32_e32 v72, v77
	v_mov_b32_e32 v76, v79
	v_mov_b32_e32 v77, v75
	v_pk_add_f32 v[72:73], v[80:81], v[72:73]
	v_mov_b32_e32 v79, v74
	v_pk_add_f32 v[72:73], v[76:77], v[72:73]
	s_nop 0
	v_pk_add_f32 v[72:73], v[78:79], v[72:73]
	ds_bpermute_b32 v75, v29, v73
	ds_bpermute_b32 v74, v29, v72
	s_waitcnt lgkmcnt(0)
	v_pk_add_f32 v[72:73], v[72:73], v[74:75]
	ds_bpermute_b32 v75, v34, v73
	ds_bpermute_b32 v74, v34, v72
	s_waitcnt lgkmcnt(0)
	v_pk_add_f32 v[72:73], v[72:73], v[74:75]
	ds_bpermute_b32 v75, v35, v73
	ds_bpermute_b32 v74, v35, v72
	s_waitcnt lgkmcnt(0)
	v_pk_add_f32 v[72:73], v[72:73], v[74:75]
	ds_bpermute_b32 v75, v36, v73
	ds_bpermute_b32 v74, v36, v72
	s_waitcnt lgkmcnt(0)
	v_pk_add_f32 v[72:73], v[72:73], v[74:75]
	ds_bpermute_b32 v75, v37, v73
	ds_bpermute_b32 v74, v37, v72
	s_waitcnt lgkmcnt(0)
	v_pk_add_f32 v[72:73], v[72:73], v[74:75]
	ds_bpermute_b32 v75, v38, v73
	ds_bpermute_b32 v74, v38, v72
	s_waitcnt lgkmcnt(0)
	v_pk_add_f32 v[72:73], v[72:73], v[74:75]
	s_nop 0
	v_pk_fma_f32 v[72:73], v[72:73], s[6:7], v[28:29] op_sel_hi:[1,0,0]
	s_nop 0
	v_mul_f32_e32 v9, 0x4b800000, v73
	v_cmp_gt_f32_e32 vcc, s7, v73
	s_nop 1
	v_cndmask_b32_e32 v9, v73, v9, vcc
	v_rsq_f32_e32 v9, v9
	s_nop 0
	v_mul_f32_e32 v39, 0x45800000, v9
	v_cndmask_b32_e32 v74, v9, v39, vcc
	v_pk_mul_f32 v[40:41], v[40:41], v[74:75] op_sel_hi:[1,0]
	v_pk_mul_f32 v[42:43], v[42:43], v[74:75] op_sel_hi:[1,0]
	v_pk_fma_f32 v[0:1], v[0:1], v[40:41], v[4:5]
	v_pk_fma_f32 v[2:3], v[2:3], v[42:43], v[6:7]
	global_store_dwordx4 v[32:33], v[0:3], off
	v_pk_mul_f32 v[40:41], v[44:45], v[74:75] op_sel_hi:[1,0]
	v_pk_mul_f32 v[42:43], v[46:47], v[74:75] op_sel_hi:[1,0]
	v_mul_f32_e32 v9, 0x4b800000, v72
	v_cmp_gt_f32_e32 vcc, s7, v72
	v_mov_b32_e32 v0, v180
	v_mov_b32_e32 v1, v181
	v_mov_b32_e32 v2, v182
	v_mov_b32_e32 v3, v183
	v_mov_b32_e32 v4, v196
	v_mov_b32_e32 v5, v197
	v_mov_b32_e32 v6, v198
	v_mov_b32_e32 v7, v199
	v_pk_fma_f32 v[0:1], v[0:1], v[40:41], v[4:5]
	v_pk_fma_f32 v[2:3], v[2:3], v[42:43], v[6:7]
	global_store_dwordx4 v[32:33], v[0:3], off offset:1024
	v_pk_mul_f32 v[40:41], v[48:49], v[74:75] op_sel_hi:[1,0]
	v_pk_mul_f32 v[42:43], v[50:51], v[74:75] op_sel_hi:[1,0]
	v_cndmask_b32_e32 v9, v72, v9, vcc
	v_rsq_f32_e32 v9, v9
	v_mov_b32_e32 v0, v184
	v_mov_b32_e32 v1, v185
	v_mov_b32_e32 v2, v186
	v_mov_b32_e32 v3, v187
	v_mov_b32_e32 v4, v200
	v_mov_b32_e32 v5, v201
	v_mov_b32_e32 v6, v202
	v_mov_b32_e32 v7, v203
	v_pk_fma_f32 v[0:1], v[40:41], v[0:1], v[4:5]
	v_pk_fma_f32 v[2:3], v[42:43], v[2:3], v[6:7]
	global_store_dwordx4 v[32:33], v[0:3], off offset:2048
	v_pk_mul_f32 v[40:41], v[52:53], v[74:75] op_sel_hi:[1,0]
	v_pk_mul_f32 v[42:43], v[54:55], v[74:75] op_sel_hi:[1,0]
	v_mov_b32_e32 v0, v188
	v_mov_b32_e32 v1, v189
	v_mov_b32_e32 v2, v190
	v_mov_b32_e32 v3, v191
	v_mov_b32_e32 v4, v204
	v_mov_b32_e32 v5, v205
	v_mov_b32_e32 v6, v206
	v_mov_b32_e32 v7, v207
	v_pk_fma_f32 v[0:1], v[40:41], v[0:1], v[4:5]
	v_pk_fma_f32 v[2:3], v[42:43], v[2:3], v[6:7]
	global_store_dwordx4 v[32:33], v[0:3], off offset:3072
	v_mul_f32_e32 v32, 0x45800000, v9
	v_cndmask_b32_e32 v32, v9, v32, vcc
	v_pk_mul_f32 v[40:41], v[56:57], v[32:33] op_sel_hi:[1,0]
	v_pk_mul_f32 v[42:43], v[58:59], v[32:33] op_sel_hi:[1,0]
	v_cmp_lt_i32_e32 vcc, s8, v8
	s_or_b64 s[0:1], vcc, s[0:1]
	v_mov_b32_e32 v0, v176
	v_mov_b32_e32 v1, v177
	v_mov_b32_e32 v2, v178
	v_mov_b32_e32 v3, v179
	v_mov_b32_e32 v4, v192
	v_mov_b32_e32 v5, v193
	v_mov_b32_e32 v6, v194
	v_mov_b32_e32 v7, v195
	v_pk_fma_f32 v[0:1], v[0:1], v[40:41], v[4:5]
	v_pk_fma_f32 v[2:3], v[2:3], v[42:43], v[6:7]
	global_store_dwordx4 v[30:31], v[0:3], off
	v_pk_mul_f32 v[40:41], v[60:61], v[32:33] op_sel_hi:[1,0]
	v_pk_mul_f32 v[42:43], v[62:63], v[32:33] op_sel_hi:[1,0]
	v_mov_b32_e32 v0, v180
	v_mov_b32_e32 v1, v181
	v_mov_b32_e32 v2, v182
	v_mov_b32_e32 v3, v183
	v_mov_b32_e32 v4, v196
	v_mov_b32_e32 v5, v197
	v_mov_b32_e32 v6, v198
	v_mov_b32_e32 v7, v199
	v_pk_fma_f32 v[0:1], v[0:1], v[40:41], v[4:5]
	v_pk_fma_f32 v[2:3], v[2:3], v[42:43], v[6:7]
	global_store_dwordx4 v[30:31], v[0:3], off offset:1024
	v_pk_mul_f32 v[40:41], v[64:65], v[32:33] op_sel_hi:[1,0]
	v_pk_mul_f32 v[42:43], v[66:67], v[32:33] op_sel_hi:[1,0]
	v_mov_b32_e32 v0, v184
	v_mov_b32_e32 v1, v185
	v_mov_b32_e32 v2, v186
	v_mov_b32_e32 v3, v187
	v_mov_b32_e32 v4, v200
	v_mov_b32_e32 v5, v201
	v_mov_b32_e32 v6, v202
	v_mov_b32_e32 v7, v203
	v_pk_fma_f32 v[0:1], v[40:41], v[0:1], v[4:5]
	v_pk_fma_f32 v[2:3], v[42:43], v[2:3], v[6:7]
	global_store_dwordx4 v[30:31], v[0:3], off offset:2048
	v_pk_mul_f32 v[40:41], v[68:69], v[32:33] op_sel_hi:[1,0]
	v_pk_mul_f32 v[32:33], v[70:71], v[32:33] op_sel_hi:[1,0]
	v_mov_b32_e32 v0, v188
	v_mov_b32_e32 v1, v189
	v_mov_b32_e32 v2, v190
	v_mov_b32_e32 v3, v191
	v_mov_b32_e32 v4, v204
	v_mov_b32_e32 v5, v205
	v_mov_b32_e32 v6, v206
	v_mov_b32_e32 v7, v207
	v_pk_fma_f32 v[0:1], v[40:41], v[0:1], v[4:5]
	v_pk_fma_f32 v[2:3], v[32:33], v[2:3], v[6:7]
	global_store_dwordx4 v[30:31], v[0:3], off offset:3072
	s_andn2_b64 exec, exec, s[0:1]
	s_cbranch_execnz .LBB0_1319
